# static priority raise: attention-phase waves 4-7 run at setprio 1 (reset at phase end)
# baseline (speedup 1.0000x reference)
; __global__ void __launch_bounds__(512, 2) fwd_mega(Args args) {
;     ...
;             for (;;) {
;                 __syncthreads();
;                 if (tid == 0) *qslot = (int)atomicAdd(ctr + 16 + l * 8 + (bx & 7), 1u);
;                 __syncthreads();
;                 const int v = *qslot;
;                 if (v >= 68) break;
;                 int ln = threadIdx.x & 63; asm volatile("" : "+v"(ln));
.LBB0_538:
	s_or_b64 exec, exec, s[2:3]
	v_mov_b32_e32 v0, s77
	s_waitcnt lgkmcnt(0)
	s_barrier
	ds_read_b32 v0, v0
	s_movk_i32 s2, 0x43
	s_waitcnt lgkmcnt(0)
	v_cmp_lt_i32_e32 vcc, s2, v0
	v_readfirstlane_b32 s4, v0
	s_mov_b64 s[2:3], -1
	s_cbranch_vccnz .LBB0_533
	v_and_b32_e32 v212, 63, v191
	v_readfirstlane_b32 s98, v191
	s_nop 3
	s_cmp_lt_u32 s98, 0x100
	s_cbranch_scc1 .Lattn_nostag
	s_sleep 20
	s_setprio 1

; __device__ __forceinline__ unsigned xb_ld(unsigned* p)              { return __hip_atomic_load(p, __ATOMIC_RELAXED, __HIP_MEMORY_SCOPE_AGENT); }
; __device__ __forceinline__ void xcd_barrier_complete(unsigned* bar, unsigned x, unsigned& nloc, unsigned& nx) {
;     const unsigned G = gridDim.x * gridDim.y * gridDim.z;
;     unsigned sum, cnt, mine, sp = 0u;
;     for (;;) {
;         sum = 0u; cnt = 0u; mine = 0u;
; #pragma unroll
;         for (unsigned j = 0; j < 16; ++j) { const unsigned c = xb_ld(&bar[XB_XCNT(j)]); sum += c; cnt += (c > 0u) ? 1u : 0u; mine = (j == x) ? c : mine; }
; __device__ __forceinline__ void xcd_barrier(const XcdBarrier& b) {
;     asm volatile("s_waitcnt vmcnt(0)" ::: "memory");
;     __syncthreads();
;     int t_o = threadIdx.x; asm volatile("" : "+v"(t_o));
;     if (t_o == 0) {
;         unsigned* bar = b.bar;
;         __builtin_amdgcn_s_waitcnt(0);
;         unsigned nloc = b.st[0], nx = b.st[1];
;         if (nloc == 0u) { xcd_barrier_complete(bar, b.x, nloc, nx); b.st[0] = nloc; b.st[1] = nx; }
.LBB0_574:
	s_setprio 0
	s_mov_b64 s[4:5], s[88:89]
	s_getreg_b32 s0, hwreg(HW_REG_XCC_ID, 0, 4)
	s_waitcnt vmcnt(0)
	v_mov_b32_e32 v0, v191
	s_waitcnt lgkmcnt(0)
	s_barrier
	s_nop 0
	v_cmp_eq_u32_e32 vcc, 0, v0
	s_and_saveexec_b64 s[2:3], vcc
	v_readlane_b32 s94, v255, 15
	v_readlane_b32 s95, v255, 16
	v_readlane_b32 s90, v255, 14
	v_readlane_b32 s91, v255, 17
	v_readlane_b32 s95, v255, 18
	v_readlane_b32 s96, v255, 26
	v_readlane_b32 s97, v255, 27
	s_cbranch_execz .LBB0_626
	v_readlane_b32 s1, v255, 8
	s_load_dwordx2 s[4:5], s[4:5], 0xa0
	s_waitcnt vmcnt(0) expcnt(0) lgkmcnt(0)
	v_mov_b32_e32 v0, s1
	ds_read_b32 v2, v0
	v_readlane_b32 s1, v255, 9
	s_and_b32 s0, s0, 15
	s_waitcnt lgkmcnt(0)
	v_cmp_ne_u32_e32 vcc, 0, v2
	v_mov_b32_e32 v0, s1
	ds_read_b32 v0, v0
	s_cbranch_vccnz .LBB0_590
	s_add_u32 s6, s4, 0x1200
	s_addc_u32 s7, s5, 0
	s_add_u32 s8, s4, 0x1400
	s_addc_u32 s9, s5, 0
	s_add_u32 s10, s4, 0x1500
	s_addc_u32 s11, s5, 0
	s_add_u32 s12, s4, 0x1600
	s_addc_u32 s13, s5, 0
	s_add_u32 s14, s4, 0x1700
	s_addc_u32 s15, s5, 0
	s_add_u32 s16, s4, 0x1800
	s_addc_u32 s17, s5, 0
	s_add_u32 s18, s4, 0x1900
	s_addc_u32 s19, s5, 0
	s_add_u32 s20, s4, 0x1a00
	s_addc_u32 s21, s5, 0
	s_add_u32 s22, s4, 0x1b00
	s_addc_u32 s23, s5, 0
	s_add_u32 s24, s4, 0x1c00
	s_addc_u32 s25, s5, 0
	s_add_u32 s26, s4, 0x1d00
	s_addc_u32 s27, s5, 0
	s_add_u32 s28, s4, 0x1e00
	s_addc_u32 s29, s5, 0
	s_add_u32 s30, s4, 0x1f00
	s_addc_u32 s31, s5, 0
	s_add_u32 s34, s4, 0x2000
	s_addc_u32 s35, s5, 0
	s_add_u32 s36, s4, 0x2100
	s_addc_u32 s37, s5, 0
	s_add_u32 s38, s4, 0x2200
	s_addc_u32 s39, s5, 0
	s_add_u32 s40, s4, 0x2300
	s_addc_u32 s41, s5, 0
	s_mov_b32 s1, 1
	s_branch .LBB0_578
